# baseline (speedup 1.0000x reference)
; #define LAS __attribute__((address_space(3)))
; __device__ __forceinline__ void ssm_unit(LAS unsigned char* lds, unsigned char* ws, int l, int b, int g, int tid) {
;     ...
;         for (int ct = 0; ct < 17; ++ct) {
;             const int c = ct * 16 + fr, cc = c < 256 ? c : 256;
;             f32x4 acc = (f32x4){0.f, 0.f, 0.f, 0.f};
; #pragma unroll
;             for (int kk = 0; kk < 8; ++kk) { const bf16x8 ub = *(const LAS bf16x8*)(lds + cc * USTR + kk * 64 + fq * 16); acc = __builtin_amdgcn_mfma_f32_16x16x32_bf16(ub, a1[kk], acc, 0, 0, 0); }
;             *(f32x4*)(ET + (size_t)(16 * wid + fr) * ECH + ct * 16 + fq * 4) = acc;
;         }
;     }
;     __syncthreads();
;     if (wid == 0) {
;         float ar, ai; lam_pow(p_lr, p_li, __expf(p_ls), 16.f, ar, ai);
.LBB0_892:
	s_cmpk_lg_i32 s0, 0x400
	s_cselect_b64 vcc, -1, 0
	v_cndmask_b32_e32 v3, v223, v2, vcc
	v_add_u32_e32 v3, v186, v3
	ds_read_b128 v[4:7], v3
	ds_read_b128 v[8:11], v3 offset:64
	ds_read_b128 v[122:125], v3 offset:128
	ds_read_b128 v[126:129], v3 offset:192
	ds_read_b128 v[130:133], v3 offset:256
	ds_read_b128 v[134:137], v3 offset:320
	ds_read_b128 v[138:141], v3 offset:384
	ds_read_b128 v[142:145], v3 offset:448
	v_add_u32_e32 v2, 0x2100, v2
	s_waitcnt lgkmcnt(7)
	v_mfma_f32_16x16x32_bf16 v[4:7], v[4:7], v[178:181], 0
	s_waitcnt lgkmcnt(6)
	v_mfma_f32_16x16x32_bf16 v[4:7], v[8:11], v[154:157], v[4:7]
	s_waitcnt lgkmcnt(5)
	v_mfma_f32_16x16x32_bf16 v[4:7], v[122:125], v[158:161], v[4:7]
	s_waitcnt lgkmcnt(4)
	v_mfma_f32_16x16x32_bf16 v[4:7], v[126:129], v[162:165], v[4:7]
	s_waitcnt lgkmcnt(3)
	v_mfma_f32_16x16x32_bf16 v[4:7], v[130:133], v[166:169], v[4:7]
	s_waitcnt lgkmcnt(2)
	v_mfma_f32_16x16x32_bf16 v[4:7], v[134:137], v[170:173], v[4:7]
	s_waitcnt lgkmcnt(1)
	v_mfma_f32_16x16x32_bf16 v[4:7], v[138:141], v[174:177], v[4:7]
	s_waitcnt lgkmcnt(0)
	v_mfma_f32_16x16x32_bf16 v[4:7], v[142:145], v[182:185], v[4:7]
	v_lshl_add_u64 v[8:9], v[0:1], 0, s[0:1]
	s_add_u32 s0, s0, 64
	s_addc_u32 s1, s1, 0
	s_cmpk_eq_i32 s0, 0x440
	s_nop 3
	global_store_dwordx4 v[8:9], v[4:7], off
	s_cbranch_scc0 .LBB0_892
	s_mul_hi_i32 s1, s76, 0x8800
	s_mul_i32 s0, s76, 0x8800
	s_cmp_lt_u32 s3, 64
	s_waitcnt vmcnt(0)
	s_barrier
	v_mul_f32_e32 v0, 0x3fb8aa3b, v242
	v_exp_f32_e32 v10, v0
	s_mov_b32 s20, 0x394ca1f9
	s_mov_b32 s21, 0x37ccf5ce
	v_mul_f32_e32 v0, v215, v10
	v_mul_f32_e32 v0, 0x41800000, v0
	v_mul_f32_e32 v1, 0x3f22f983, v0
	v_rndne_f32_e32 v1, v1
	v_fmac_f32_e32 v0, 0xbfc90000, v1
	v_fmac_f32_e32 v0, 0xb9fda000, v1
	v_fmac_f32_e32 v0, 0xb3a22169, v1
	v_cvt_i32_f32_e32 v11, v1
	v_mul_f32_e32 v1, v0, v0
	v_mov_b32_e32 v2, v1
	v_pk_fma_f32 v[4:5], v[0:1], s[20:21], v[198:199]
	v_pk_fma_f32 v[8:9], v[2:3], s[20:21], v[200:201] op_sel_hi:[0,1,1] neg_lo:[1,0,0] neg_hi:[1,0,0]
	s_mov_b32 s20, 0xbe2aaaa3
	v_fma_f32 v12, v1, -0.5, 1.0
	v_mov_b32_e32 v9, v5
	s_mov_b32 s21, 0x3d2aaaa5
	v_pk_mul_f32 v[6:7], v[0:1], v[2:3] op_sel_hi:[1,0]
	v_pk_fma_f32 v[2:3], v[2:3], v[8:9], s[20:21] op_sel_hi:[0,1,1]
	v_mov_b32_e32 v1, v12
	v_pk_fma_f32 v[8:9], v[6:7], v[2:3], v[0:1]
	v_and_b32_e32 v0, 3, v11
	v_cmp_lt_i32_e32 vcc, 0, v0
	v_mov_b32_e32 v11, v9
	s_and_saveexec_b64 s[20:21], vcc
	s_cbranch_execz .LBB0_900
	v_cmp_ne_u32_e32 vcc, 1, v0
	v_xor_b32_e32 v11, 0x80000000, v8
	s_and_saveexec_b64 s[22:23], vcc
	s_xor_b64 s[22:23], exec, s[22:23]
	v_cmp_eq_u32_e32 vcc, 2, v0
	s_nop 1
	v_cndmask_b32_e32 v0, v9, v8, vcc
	v_xor_b32_e32 v0, 0x80000000, v0
	v_cndmask_b32_e64 v11, v8, -v9, vcc
	v_mov_b32_e32 v8, v0
	s_andn2_saveexec_b64 s[22:23], s[22:23]
	v_mov_b32_e32 v8, v9
	s_or_b64 exec, exec, s[22:23]
